# EpiConv: wr==0 waves pre-touch rowss panel + conv weight cache lines (3 dword loads into a dead VGPR) while waiting at the resync barrier, so the epilogue loads hit L1
# baseline (speedup 1.0000x reference)
.LBB0_453:
	s_add_u32 s24, s22, 0xfffc0080
	s_addc_u32 s25, s23, -1
	s_add_i32 s76, 0, 0x10000
	s_cmp_eq_u32 vcc_lo, 12
	s_cselect_b32 s29, s30, s25
	s_cselect_b32 s28, s31, s24
	v_add_u32_e32 v114, s76, v220
	s_cselect_b32 s25, s69, s99
	s_cselect_b32 s24, s75, s81
	s_add_i32 vcc_hi, 0, 0x14000
	ds_read_b128 v[106:109], v114
	ds_read_b128 v[110:113], v114 offset:1024
	ds_read_b128 v[128:131], v114 offset:2048
	ds_read_b128 v[132:135], v114 offset:3072
	v_add_u32_e32 v114, vcc_hi, v220
	ds_read_b128 v[136:139], v114
	ds_read_b128 v[158:161], v114 offset:1024
	ds_read_b128 v[162:165], v114 offset:2048
	ds_read_b128 v[166:169], v114 offset:3072
	s_add_i32 m0, s57, 0xc000
	ds_read_b128 v[170:173], v234
	ds_read_b128 v[174:177], v234 offset:1024
	ds_read_b128 v[178:181], v234 offset:2048
	ds_read_b128 v[198:201], v234 offset:3072
	ds_read_b128 v[202:205], v234 offset:4096
	ds_read_b128 v[206:209], v234 offset:5120
	ds_read_b128 v[210:213], v234 offset:6144
	ds_read_b128 v[214:217], v234 offset:7168
	global_load_lds_dwordx4 v194, s[22:23]
	s_add_i32 m0, s57, 0xe000
	s_nop 0
	global_load_lds_dwordx4 v196, s[22:23]
	s_waitcnt vmcnt(8)
	s_waitcnt lgkmcnt(0)
	s_barrier
	s_setprio 1
	v_mfma_f32_16x16x32_bf16 v[124:127], v[106:109], v[170:173], v[124:127]
	v_mfma_f32_16x16x32_bf16 v[98:101], v[128:131], v[170:173], v[98:101]
	v_mfma_f32_16x16x32_bf16 v[154:157], v[106:109], v[178:181], v[154:157]
	v_mfma_f32_16x16x32_bf16 v[58:61], v[128:131], v[178:181], v[58:61]
	v_mfma_f32_16x16x32_bf16 v[146:149], v[106:109], v[202:205], v[146:149]
	v_mfma_f32_16x16x32_bf16 v[46:49], v[128:131], v[202:205], v[46:49]
	v_mfma_f32_16x16x32_bf16 v[102:105], v[106:109], v[210:213], v[102:105]
	v_mfma_f32_16x16x32_bf16 v[54:57], v[128:131], v[210:213], v[54:57]
	v_mfma_f32_16x16x32_bf16 v[124:127], v[110:113], v[174:177], v[124:127]
	v_mfma_f32_16x16x32_bf16 v[98:101], v[132:135], v[174:177], v[98:101]
	v_mfma_f32_16x16x32_bf16 v[154:157], v[110:113], v[198:201], v[154:157]
	v_mfma_f32_16x16x32_bf16 v[58:61], v[132:135], v[198:201], v[58:61]
	v_mfma_f32_16x16x32_bf16 v[146:149], v[110:113], v[206:209], v[146:149]
	v_mfma_f32_16x16x32_bf16 v[46:49], v[132:135], v[206:209], v[46:49]
	v_mfma_f32_16x16x32_bf16 v[102:105], v[110:113], v[214:217], v[102:105]
	v_mfma_f32_16x16x32_bf16 v[54:57], v[132:135], v[214:217], v[54:57]
	v_mfma_f32_16x16x32_bf16 v[120:123], v[136:139], v[170:173], v[120:123]
	v_mfma_f32_16x16x32_bf16 v[94:97], v[162:165], v[170:173], v[94:97]
	v_mfma_f32_16x16x32_bf16 v[150:153], v[136:139], v[178:181], v[150:153]
	v_mfma_f32_16x16x32_bf16 v[50:53], v[162:165], v[178:181], v[50:53]
	v_mfma_f32_16x16x32_bf16 v[140:143], v[136:139], v[202:205], v[142:145]
	v_mfma_f32_16x16x32_bf16 v[42:45], v[162:165], v[202:205], v[42:45]
	v_mfma_f32_16x16x32_bf16 v[114:117], v[136:139], v[210:213], v[116:119]
	v_mfma_f32_16x16x32_bf16 v[38:41], v[162:165], v[210:213], v[38:41]
	v_mfma_f32_16x16x32_bf16 v[120:123], v[158:161], v[174:177], v[120:123]
	v_mfma_f32_16x16x32_bf16 v[94:97], v[166:169], v[174:177], v[94:97]
	v_mfma_f32_16x16x32_bf16 v[150:153], v[158:161], v[198:201], v[150:153]
	v_mfma_f32_16x16x32_bf16 v[50:53], v[166:169], v[198:201], v[50:53]
	v_mfma_f32_16x16x32_bf16 v[140:143], v[158:161], v[206:209], v[140:143]
	v_mfma_f32_16x16x32_bf16 v[42:45], v[166:169], v[206:209], v[42:45]
	v_mfma_f32_16x16x32_bf16 v[114:117], v[158:161], v[214:217], v[114:117]
	v_mfma_f32_16x16x32_bf16 v[38:41], v[166:169], v[214:217], v[38:41]
	s_setprio 0
	s_barrier
	s_add_i32 s76, s76, s42
	s_mov_b32 m0, s76
	ds_read_b128 v[170:173], v234 offset:16384
	ds_read_b128 v[174:177], v234 offset:17408
	ds_read_b128 v[178:181], v234 offset:18432
	ds_read_b128 v[198:201], v234 offset:19456
	ds_read_b128 v[202:205], v234 offset:20480
	ds_read_b128 v[206:209], v234 offset:21504
	ds_read_b128 v[210:213], v234 offset:22528
	ds_read_b128 v[214:217], v234 offset:23552
	global_load_lds_dwordx4 v0, s[24:25]
	s_add_i32 m0, s76, 0x2000
	s_add_u32 s76, s24, 0x40000
	s_addc_u32 s77, s25, 0
	s_add_i32 vcc_hi, vcc_hi, s42
	global_load_lds_dwordx4 v192, s[24:25]
	s_mov_b32 m0, vcc_hi
	s_nop 0
	global_load_lds_dwordx4 v0, s[76:77]
	s_add_i32 m0, vcc_hi, 0x2000
	s_nop 0
	global_load_lds_dwordx4 v192, s[76:77]
	s_mov_b32 m0, s57
	s_nop 0
	global_load_lds_dwordx4 v188, s[28:29]
	s_mov_b32 m0, s66
	s_nop 0
	global_load_lds_dwordx4 v190, s[28:29]
	s_waitcnt vmcnt(8)
	s_waitcnt lgkmcnt(0)
	s_barrier
	s_setprio 1
	v_mfma_f32_16x16x32_bf16 v[86:89], v[106:109], v[170:173], v[86:89]
	v_mfma_f32_16x16x32_bf16 v[30:33], v[128:131], v[170:173], v[30:33]
	v_mfma_f32_16x16x32_bf16 v[78:81], v[106:109], v[178:181], v[78:81]
	v_mfma_f32_16x16x32_bf16 v[22:25], v[128:131], v[178:181], v[22:25]
	v_mfma_f32_16x16x32_bf16 v[70:73], v[106:109], v[202:205], v[70:73]
	v_mfma_f32_16x16x32_bf16 v[14:17], v[128:131], v[202:205], v[14:17]
	v_mfma_f32_16x16x32_bf16 v[90:93], v[106:109], v[210:213], v[90:93]
	v_mfma_f32_16x16x32_bf16 v[34:37], v[128:131], v[210:213], v[34:37]
	v_mfma_f32_16x16x32_bf16 v[86:89], v[110:113], v[174:177], v[86:89]
	v_mfma_f32_16x16x32_bf16 v[30:33], v[132:135], v[174:177], v[30:33]
	v_mfma_f32_16x16x32_bf16 v[78:81], v[110:113], v[198:201], v[78:81]
	v_mfma_f32_16x16x32_bf16 v[22:25], v[132:135], v[198:201], v[22:25]
	v_mfma_f32_16x16x32_bf16 v[70:73], v[110:113], v[206:209], v[70:73]
	v_mfma_f32_16x16x32_bf16 v[14:17], v[132:135], v[206:209], v[14:17]
	v_mfma_f32_16x16x32_bf16 v[90:93], v[110:113], v[214:217], v[90:93]
	v_mfma_f32_16x16x32_bf16 v[34:37], v[132:135], v[214:217], v[34:37]
	v_mfma_f32_16x16x32_bf16 v[82:85], v[136:139], v[170:173], v[82:85]
	v_mfma_f32_16x16x32_bf16 v[26:29], v[162:165], v[170:173], v[26:29]
	v_mfma_f32_16x16x32_bf16 v[74:77], v[136:139], v[178:181], v[74:77]
	v_mfma_f32_16x16x32_bf16 v[18:21], v[162:165], v[178:181], v[18:21]
	v_mfma_f32_16x16x32_bf16 v[66:69], v[136:139], v[202:205], v[66:69]
	v_mfma_f32_16x16x32_bf16 v[10:13], v[162:165], v[202:205], v[10:13]
	v_mfma_f32_16x16x32_bf16 v[62:65], v[136:139], v[210:213], v[62:65]
	v_mfma_f32_16x16x32_bf16 v[6:9], v[162:165], v[210:213], v[6:9]
	v_mfma_f32_16x16x32_bf16 v[82:85], v[158:161], v[174:177], v[82:85]
	v_mfma_f32_16x16x32_bf16 v[26:29], v[166:169], v[174:177], v[26:29]
	v_mfma_f32_16x16x32_bf16 v[74:77], v[158:161], v[198:201], v[74:77]
	v_mfma_f32_16x16x32_bf16 v[18:21], v[166:169], v[198:201], v[18:21]
	v_mfma_f32_16x16x32_bf16 v[66:69], v[158:161], v[206:209], v[66:69]
	v_mfma_f32_16x16x32_bf16 v[10:13], v[166:169], v[206:209], v[10:13]
	v_mfma_f32_16x16x32_bf16 v[62:65], v[158:161], v[214:217], v[62:65]
	v_mfma_f32_16x16x32_bf16 v[6:9], v[166:169], v[214:217], v[6:9]
	s_setprio 0
	s_barrier
	s_add_i32 s76, 0, 0x18000
	v_add_u32_e32 v118, s76, v220
	s_add_i32 s77, 0, 0x1c000
	ds_read_b128 v[106:109], v118
	ds_read_b128 v[110:113], v118 offset:1024
	ds_read_b128 v[128:131], v118 offset:2048
	ds_read_b128 v[132:135], v118 offset:3072
	v_add_u32_e32 v118, s77, v220
	ds_read_b128 v[136:139], v118
	ds_read_b128 v[158:161], v118 offset:1024
	ds_read_b128 v[162:165], v118 offset:2048
	ds_read_b128 v[166:169], v118 offset:3072
	s_add_u32 s28, s28, 0x40000
	s_addc_u32 s29, s29, 0
	s_mov_b32 m0, s67
	ds_read_b128 v[170:173], v234 offset:32768
	ds_read_b128 v[174:177], v234 offset:33792
	ds_read_b128 v[178:181], v234 offset:34816
	ds_read_b128 v[198:201], v234 offset:35840
	ds_read_b128 v[202:205], v234 offset:36864
	ds_read_b128 v[206:209], v234 offset:37888
	ds_read_b128 v[210:213], v234 offset:38912
	ds_read_b128 v[214:217], v234 offset:39936
	global_load_lds_dwordx4 v188, s[28:29]
	s_mov_b32 m0, s44
	s_nop 0
	global_load_lds_dwordx4 v190, s[28:29]
	s_waitcnt vmcnt(8)
	s_waitcnt lgkmcnt(0)
	s_barrier
	s_setprio 1
	v_mfma_f32_16x16x32_bf16 v[124:127], v[106:109], v[170:173], v[124:127]
	v_mfma_f32_16x16x32_bf16 v[98:101], v[128:131], v[170:173], v[98:101]
	v_mfma_f32_16x16x32_bf16 v[154:157], v[106:109], v[178:181], v[154:157]
	v_mfma_f32_16x16x32_bf16 v[58:61], v[128:131], v[178:181], v[58:61]
	v_mfma_f32_16x16x32_bf16 v[144:147], v[106:109], v[202:205], v[146:149]
	v_mfma_f32_16x16x32_bf16 v[46:49], v[128:131], v[202:205], v[46:49]
	v_mfma_f32_16x16x32_bf16 v[102:105], v[106:109], v[210:213], v[102:105]
	v_mfma_f32_16x16x32_bf16 v[54:57], v[128:131], v[210:213], v[54:57]
	v_mfma_f32_16x16x32_bf16 v[124:127], v[110:113], v[174:177], v[124:127]
	v_mfma_f32_16x16x32_bf16 v[98:101], v[132:135], v[174:177], v[98:101]
	v_mfma_f32_16x16x32_bf16 v[154:157], v[110:113], v[198:201], v[154:157]
	v_mfma_f32_16x16x32_bf16 v[58:61], v[132:135], v[198:201], v[58:61]
	v_mfma_f32_16x16x32_bf16 v[146:149], v[110:113], v[206:209], v[144:147]
	v_mfma_f32_16x16x32_bf16 v[46:49], v[132:135], v[206:209], v[46:49]
	v_mfma_f32_16x16x32_bf16 v[102:105], v[110:113], v[214:217], v[102:105]
	v_mfma_f32_16x16x32_bf16 v[54:57], v[132:135], v[214:217], v[54:57]
	v_mfma_f32_16x16x32_bf16 v[118:121], v[136:139], v[170:173], v[120:123]
	v_mfma_f32_16x16x32_bf16 v[94:97], v[162:165], v[170:173], v[94:97]
	v_mfma_f32_16x16x32_bf16 v[150:153], v[136:139], v[178:181], v[150:153]
	v_mfma_f32_16x16x32_bf16 v[50:53], v[162:165], v[178:181], v[50:53]
	v_mfma_f32_16x16x32_bf16 v[140:143], v[136:139], v[202:205], v[140:143]
	v_mfma_f32_16x16x32_bf16 v[42:45], v[162:165], v[202:205], v[42:45]
	v_mfma_f32_16x16x32_bf16 v[114:117], v[136:139], v[210:213], v[114:117]
	v_mfma_f32_16x16x32_bf16 v[38:41], v[162:165], v[210:213], v[38:41]
	v_mfma_f32_16x16x32_bf16 v[120:123], v[158:161], v[174:177], v[118:121]
	v_mfma_f32_16x16x32_bf16 v[94:97], v[166:169], v[174:177], v[94:97]
	v_mfma_f32_16x16x32_bf16 v[150:153], v[158:161], v[198:201], v[150:153]
	v_mfma_f32_16x16x32_bf16 v[50:53], v[166:169], v[198:201], v[50:53]
	v_mfma_f32_16x16x32_bf16 v[142:145], v[158:161], v[206:209], v[140:143]
	v_mfma_f32_16x16x32_bf16 v[42:45], v[166:169], v[206:209], v[42:45]
	v_mfma_f32_16x16x32_bf16 v[116:119], v[158:161], v[214:217], v[114:117]
	v_mfma_f32_16x16x32_bf16 v[38:41], v[166:169], v[214:217], v[38:41]
	s_setprio 0
	s_barrier
	s_add_i32 s100, s76, s42
	s_mov_b32 m0, s100
	ds_read_b128 v[170:173], v234 offset:49152
	ds_read_b128 v[174:177], v234 offset:50176
	ds_read_b128 v[178:181], v234 offset:51200
	ds_read_b128 v[198:201], v234 offset:52224
	ds_read_b128 v[202:205], v234 offset:53248
	ds_read_b128 v[206:209], v234 offset:54272
	ds_read_b128 v[210:213], v234 offset:55296
	ds_read_b128 v[214:217], v234 offset:56320
	s_add_u32 s24, s24, 0x80
	s_addc_u32 s25, s25, 0
	global_load_lds_dwordx4 v0, s[24:25]
	s_add_i32 m0, s100, 0x2000
	s_add_i32 s100, s77, s42
	global_load_lds_dwordx4 v192, s[24:25]
	s_add_u32 s24, s24, 0x40000
	s_addc_u32 s25, s25, 0
	s_mov_b32 m0, s100
	s_add_i32 s100, s100, 0x2000
	global_load_lds_dwordx4 v0, s[24:25]
	s_mov_b32 m0, s100
	s_add_u32 s28, s28, 0xfffc0080
	s_addc_u32 s29, s29, -1
	global_load_lds_dwordx4 v192, s[24:25]
	s_mov_b32 m0, s45
	s_nop 0
	global_load_lds_dwordx4 v188, s[28:29]
	s_mov_b32 m0, s70
	s_nop 0
	global_load_lds_dwordx4 v190, s[28:29]
	s_waitcnt vmcnt(8)
	s_waitcnt lgkmcnt(0)
	s_barrier
	s_setprio 1
	v_mfma_f32_16x16x32_bf16 v[86:89], v[106:109], v[170:173], v[86:89]
	v_mfma_f32_16x16x32_bf16 v[30:33], v[128:131], v[170:173], v[30:33]
	v_mfma_f32_16x16x32_bf16 v[78:81], v[106:109], v[178:181], v[78:81]
	v_mfma_f32_16x16x32_bf16 v[22:25], v[128:131], v[178:181], v[22:25]
	v_mfma_f32_16x16x32_bf16 v[70:73], v[106:109], v[202:205], v[70:73]
	v_mfma_f32_16x16x32_bf16 v[14:17], v[128:131], v[202:205], v[14:17]
	v_mfma_f32_16x16x32_bf16 v[90:93], v[106:109], v[210:213], v[90:93]
	v_mfma_f32_16x16x32_bf16 v[34:37], v[128:131], v[210:213], v[34:37]
	v_mfma_f32_16x16x32_bf16 v[86:89], v[110:113], v[174:177], v[86:89]
	v_mfma_f32_16x16x32_bf16 v[30:33], v[132:135], v[174:177], v[30:33]
	v_mfma_f32_16x16x32_bf16 v[78:81], v[110:113], v[198:201], v[78:81]
	v_mfma_f32_16x16x32_bf16 v[22:25], v[132:135], v[198:201], v[22:25]
	v_mfma_f32_16x16x32_bf16 v[70:73], v[110:113], v[206:209], v[70:73]
	v_mfma_f32_16x16x32_bf16 v[14:17], v[132:135], v[206:209], v[14:17]
	v_mfma_f32_16x16x32_bf16 v[90:93], v[110:113], v[214:217], v[90:93]
	v_mfma_f32_16x16x32_bf16 v[34:37], v[132:135], v[214:217], v[34:37]
	v_mfma_f32_16x16x32_bf16 v[82:85], v[136:139], v[170:173], v[82:85]
	v_mfma_f32_16x16x32_bf16 v[26:29], v[162:165], v[170:173], v[26:29]
	v_mfma_f32_16x16x32_bf16 v[74:77], v[136:139], v[178:181], v[74:77]
	v_mfma_f32_16x16x32_bf16 v[18:21], v[162:165], v[178:181], v[18:21]
	v_mfma_f32_16x16x32_bf16 v[66:69], v[136:139], v[202:205], v[66:69]
	v_mfma_f32_16x16x32_bf16 v[10:13], v[162:165], v[202:205], v[10:13]
	v_mfma_f32_16x16x32_bf16 v[62:65], v[136:139], v[210:213], v[62:65]
	v_mfma_f32_16x16x32_bf16 v[6:9], v[162:165], v[210:213], v[6:9]
	v_mfma_f32_16x16x32_bf16 v[82:85], v[158:161], v[174:177], v[82:85]
	v_mfma_f32_16x16x32_bf16 v[26:29], v[166:169], v[174:177], v[26:29]
	v_mfma_f32_16x16x32_bf16 v[74:77], v[158:161], v[198:201], v[74:77]
	v_mfma_f32_16x16x32_bf16 v[18:21], v[166:169], v[198:201], v[18:21]
	v_mfma_f32_16x16x32_bf16 v[66:69], v[158:161], v[206:209], v[66:69]
	v_mfma_f32_16x16x32_bf16 v[10:13], v[166:169], v[206:209], v[10:13]
	v_mfma_f32_16x16x32_bf16 v[62:65], v[158:161], v[214:217], v[62:65]
	v_mfma_f32_16x16x32_bf16 v[6:9], v[166:169], v[214:217], v[6:9]
	s_setprio 0
	s_barrier
	s_add_i32 vcc_lo, vcc_lo, 2
	s_add_u32 s22, s22, 0x100
	s_addc_u32 s23, s23, 0
	s_add_u32 s81, s81, 0x100
	s_addc_u32 s99, s99, 0
	s_cmp_gt_u32 vcc_lo, 13
	s_cbranch_scc0 .LBB0_453
	s_and_b64 vcc, exec, s[26:27]
	s_cbranch_vccz .LBB0_456
	s_load_dwordx4 s[28:31], s[0:1], 0x68
	v_mbcnt_lo_u32_b32 v235, -1, 0
	v_mbcnt_hi_u32_b32 v235, -1, v235
	s_lshl_b32 s22, s73, 12
	s_add_u32 s22, s48, s22
	s_addc_u32 s23, s49, 0
	v_lshlrev_b32_e32 v236, 6, v235
	global_load_dword v240, v236, s[22:23]
	v_lshrrev_b32_e32 v241, 4, v235
	v_and_b32_e32 v236, 15, v235
	v_min_u32_e32 v241, 2, v241
	s_lshl_b32 s76, s68, 9
	v_mul_u32_u24_e32 v241, 0x2c00, v241
	v_lshl_add_u32 v236, v236, 5, s76
	s_mul_i32 s24, s56, 0x8400
	s_mul_i32 s25, s56, 0x2c00
	v_add_u32_e32 v241, v241, v236
	s_waitcnt lgkmcnt(0)
	s_add_u32 s22, s28, s24
	s_addc_u32 s23, s29, 0
	s_add_u32 s24, s30, s25
	s_addc_u32 s25, s31, 0
	global_load_dword v240, v241, s[22:23]
	global_load_dword v240, v236, s[24:25]
	s_barrier
